# row phases R0, R2_0, R1_1: loads of all four rows of a wave issued before the row loop (they were load-wait-compute one row at a time)
# speedup vs baseline: 1.0019x; 1.0019x over previous
.LBB0_114:
	v_lshl_add_u32 v0, v71, 2, v69
	v_ashrrev_i32_e32 v0, 11, v0
	v_add_u32_e32 v0, 1, v0
	v_cmp_lt_i32_e32 vcc, s2, v71
	s_mov_b32 s14, 0
	s_nop 0
	v_cndmask_b32_e32 v0, 0, v0, vcc
	v_mul_hi_i32_i24_e32 v1, 0x6000, v0
	v_mul_i32_i24_e32 v0, 0x6000, v0
	v_lshl_add_u64 v[8:9], s[56:57], 0, v[0:1]
	v_lshl_add_u64 v[10:11], v[8:9], 0, s[8:9]
	v_lshl_add_u64 v[28:29], v[8:9], 0, v[32:33]
	v_lshl_add_u64 v[8:9], v[10:11], 0, v[32:33]
	global_load_dwordx4 v[0:3], v[36:37], off offset:16
	global_load_dwordx4 v[4:7], v[36:37], off
	global_load_dwordx4 v[46:49], v[8:9], off offset:16
	global_load_dwordx4 v[42:45], v[8:9], off
	v_lshl_add_u64 v[8:9], v[10:11], 0, v[38:39]
	global_load_dwordx4 v[54:57], v[8:9], off offset:16
	global_load_dwordx4 v[50:53], v[8:9], off
	s_nop 0
	global_load_dwordx4 v[8:11], v[28:29], off offset:16
	global_load_dwordx4 v[12:15], v[28:29], off
	global_load_dwordx4 v[16:19], v[36:37], off offset:2064
	global_load_dwordx4 v[20:23], v[36:37], off offset:2048
	global_load_dwordx4 v[24:27], v[28:29], off offset:2064
	s_nop 0
	global_load_dwordx4 v[28:31], v[28:29], off offset:2048
	s_waitcnt vmcnt(7)
	v_pk_add_f32 v[54:55], v[54:55], 1.0 op_sel_hi:[1,0]
	s_waitcnt vmcnt(6)
	v_pk_add_f32 v[50:51], v[50:51], 1.0 op_sel_hi:[1,0]
	v_pk_add_f32 v[46:47], v[46:47], 1.0 op_sel_hi:[1,0]
	v_pk_add_f32 v[40:41], v[44:45], 1.0 op_sel_hi:[1,0]
	v_pk_add_f32 v[42:43], v[42:43], 1.0 op_sel_hi:[1,0]
	v_pk_add_f32 v[44:45], v[48:49], 1.0 op_sel_hi:[1,0]
	v_pk_add_f32 v[48:49], v[52:53], 1.0 op_sel_hi:[1,0]
	v_pk_add_f32 v[52:53], v[56:57], 1.0 op_sel_hi:[1,0]
	v_readfirstlane_b32 s60, v68
	s_nop 1
	s_cmp_gt_u32 s60, 0xfff
	s_cselect_b32 s62, s38, s36
	s_cselect_b32 s63, s39, s37
	s_and_b32 s60, s60, 0xfff
	s_lshl_b32 s60, s60, 12
	s_add_u32 s62, s62, s60
	s_addc_u32 s63, s63, 0
	global_load_dwordx4 v[100:103], v32, s[62:63] nt
	global_load_dwordx4 v[104:107], v32, s[62:63] offset:16 nt
	global_load_dwordx4 v[108:111], v32, s[62:63] offset:2048 nt
	global_load_dwordx4 v[112:115], v32, s[62:63] offset:2064 nt
	s_add_u32 s62, s62, 0x1000
	s_addc_u32 s63, s63, 0
	global_load_dwordx4 v[116:119], v32, s[62:63] nt
	global_load_dwordx4 v[120:123], v32, s[62:63] offset:16 nt
	global_load_dwordx4 v[124:127], v32, s[62:63] offset:2048 nt
	global_load_dwordx4 v[128:131], v32, s[62:63] offset:2064 nt
	s_add_u32 s62, s62, 0x1000
	s_addc_u32 s63, s63, 0
	global_load_dwordx4 v[170:173], v32, s[62:63] nt
	global_load_dwordx4 v[174:177], v32, s[62:63] offset:16 nt
	global_load_dwordx4 v[178:181], v32, s[62:63] offset:2048 nt
	global_load_dwordx4 v[182:185], v32, s[62:63] offset:2064 nt
	s_add_u32 s62, s62, 0x1000
	s_addc_u32 s63, s63, 0
	global_load_dwordx4 v[186:189], v32, s[62:63] nt
	global_load_dwordx4 v[190:193], v32, s[62:63] offset:16 nt
	global_load_dwordx4 v[194:197], v32, s[62:63] offset:2048 nt
	global_load_dwordx4 v[198:201], v32, s[62:63] offset:2064 nt
	s_branch .LBB0_116
.LBB0_115:
	s_or_b64 exec, exec, s[12:13]
	v_lshl_add_u64 v[56:57], v[60:61], 0, v[32:33]
	s_cmp_eq_u32 s14, 0
	s_cbranch_scc0 .Lr0pfB_b
	s_waitcnt vmcnt(10)
	v_mov_b32_e32 v72, v116
	v_mov_b32_e32 v73, v117
	v_mov_b32_e32 v74, v118
	v_mov_b32_e32 v75, v119
	v_mov_b32_e32 v76, v120
	v_mov_b32_e32 v77, v121
	v_mov_b32_e32 v78, v122
	v_mov_b32_e32 v79, v123
	v_mov_b32_e32 v80, v124
	v_mov_b32_e32 v81, v125
	v_mov_b32_e32 v82, v126
	v_mov_b32_e32 v83, v127
	v_mov_b32_e32 v84, v128
	v_mov_b32_e32 v85, v129
	v_mov_b32_e32 v86, v130
	v_mov_b32_e32 v87, v131
	s_branch .Lr0pfB_d
.Lr0pfB_b:
	s_waitcnt vmcnt(6)
	v_mov_b32_e32 v72, v186
	v_mov_b32_e32 v73, v187
	v_mov_b32_e32 v74, v188
	v_mov_b32_e32 v75, v189
	v_mov_b32_e32 v76, v190
	v_mov_b32_e32 v77, v191
	v_mov_b32_e32 v78, v192
	v_mov_b32_e32 v79, v193
	v_mov_b32_e32 v80, v194
	v_mov_b32_e32 v81, v195
	v_mov_b32_e32 v82, v196
	v_mov_b32_e32 v83, v197
	v_mov_b32_e32 v84, v198
	v_mov_b32_e32 v85, v199
	v_mov_b32_e32 v86, v200
	v_mov_b32_e32 v87, v201
.Lr0pfB_d:
	s_add_i32 s14, s14, 2
	s_cmp_eq_u32 s14, 4
	s_nop 0
	v_mov_b32_e32 v60, v73
	s_nop 0
	v_mov_b32_e32 v61, v77
	v_mov_b32_e32 v56, v72
	v_mov_b32_e32 v57, v76
	s_nop 0
	v_mov_b32_e32 v94, v81
	s_nop 0
	v_mov_b32_e32 v95, v85
	v_pk_mul_f32 v[60:61], v[60:61], v[60:61]
	v_mov_b32_e32 v88, v74
	v_mov_b32_e32 v89, v78
	v_mov_b32_e32 v92, v80
	v_mov_b32_e32 v93, v84
	v_pk_mul_f32 v[94:95], v[94:95], v[94:95]
	v_pk_fma_f32 v[56:57], v[56:57], v[56:57], v[60:61]
	v_mov_b32_e32 v90, v75
	v_mov_b32_e32 v91, v79
	v_mov_b32_e32 v96, v82
	v_mov_b32_e32 v97, v86
	v_pk_fma_f32 v[60:61], v[92:93], v[92:93], v[94:95]
	v_pk_fma_f32 v[56:57], v[88:89], v[88:89], v[56:57]
	v_mov_b32_e32 v98, v83
	v_mov_b32_e32 v99, v87
	v_pk_fma_f32 v[60:61], v[96:97], v[96:97], v[60:61]
	v_pk_fma_f32 v[56:57], v[90:91], v[90:91], v[56:57]
	v_pk_fma_f32 v[60:61], v[98:99], v[98:99], v[60:61]
	v_add_f32_e32 v56, v56, v57
	v_add_f32_e32 v56, v56, v60
	v_add_f32_e32 v56, v56, v61
	ds_bpermute_b32 v57, v62, v56
	s_waitcnt lgkmcnt(0)
	v_add_f32_e32 v56, v56, v57
	ds_bpermute_b32 v57, v63, v56
	s_waitcnt lgkmcnt(0)
	v_add_f32_e32 v56, v56, v57
	ds_bpermute_b32 v57, v64, v56
	s_waitcnt lgkmcnt(0)
	v_add_f32_e32 v56, v56, v57
	ds_bpermute_b32 v57, v65, v56
	s_waitcnt lgkmcnt(0)
	v_add_f32_e32 v56, v56, v57
	ds_bpermute_b32 v57, v66, v56
	s_waitcnt lgkmcnt(0)
	v_add_f32_e32 v60, v56, v57
	ds_bpermute_b32 v61, v67, v60
	v_lshlrev_b64 v[56:57], 11, v[58:59]
	s_waitcnt lgkmcnt(0)
	v_add_f32_e32 v58, v60, v61
	v_fmamk_f32 v58, v58, 0x3a800000, v70
	v_mul_f32_e32 v59, 0x4b800000, v58
	v_cmp_gt_f32_e32 vcc, s10, v58
	v_lshl_add_u64 v[60:61], v[34:35], 0, v[56:57]
	s_nop 0
	v_cndmask_b32_e32 v58, v58, v59, vcc
	v_rsq_f32_e32 v58, v58
	s_nop 0
	v_mul_f32_e32 v56, 0x45800000, v58
	v_cndmask_b32_e32 v56, v58, v56, vcc
	v_pk_mul_f32 v[58:59], v[74:75], v[56:57] op_sel_hi:[1,0]
	v_pk_mul_f32 v[72:73], v[72:73], v[56:57] op_sel_hi:[1,0]
	v_pk_mul_f32 v[74:75], v[78:79], v[56:57] op_sel_hi:[1,0]
	v_pk_mul_f32 v[76:77], v[76:77], v[56:57] op_sel_hi:[1,0]
	v_pk_mul_f32 v[78:79], v[82:83], v[56:57] op_sel_hi:[1,0]
	v_pk_mul_f32 v[80:81], v[80:81], v[56:57] op_sel_hi:[1,0]
	v_pk_mul_f32 v[82:83], v[86:87], v[56:57] op_sel_hi:[1,0]
	v_pk_mul_f32 v[56:57], v[84:85], v[56:57] op_sel_hi:[1,0]
	v_pk_mul_f32 v[72:73], v[4:5], v[72:73]
	v_pk_mul_f32 v[58:59], v[6:7], v[58:59]
	v_pk_mul_f32 v[76:77], v[0:1], v[76:77]
	v_pk_mul_f32 v[74:75], v[2:3], v[74:75]
	v_pk_mul_f32 v[80:81], v[20:21], v[80:81]
	v_pk_mul_f32 v[78:79], v[22:23], v[78:79]
	v_pk_mul_f32 v[56:57], v[16:17], v[56:57]
	v_pk_mul_f32 v[82:83], v[18:19], v[82:83]
	v_pk_fma_f32 v[58:59], v[40:41], v[58:59], v[14:15]
	v_pk_fma_f32 v[72:73], v[42:43], v[72:73], v[12:13]
	v_pk_fma_f32 v[74:75], v[44:45], v[74:75], v[10:11]
	v_pk_fma_f32 v[76:77], v[46:47], v[76:77], v[8:9]
	v_pk_fma_f32 v[78:79], v[48:49], v[78:79], v[30:31]
	v_pk_fma_f32 v[80:81], v[50:51], v[80:81], v[28:29]
	v_pk_fma_f32 v[82:83], v[52:53], v[82:83], v[26:27]
	v_pk_fma_f32 v[84:85], v[54:55], v[56:57], v[24:25]
	v_cvt_pk_bf16_f32 v56, v72, v73
	v_cvt_pk_bf16_f32 v57, v58, v59
	v_cvt_pk_bf16_f32 v58, v76, v77
	v_cvt_pk_bf16_f32 v59, v74, v75
	v_cvt_pk_bf16_f32 v72, v80, v81
	v_cvt_pk_bf16_f32 v73, v78, v79
	v_cvt_pk_bf16_f32 v74, v84, v85
	v_cvt_pk_bf16_f32 v75, v82, v83
	global_store_dwordx4 v[60:61], v[56:59], off sc1
	global_store_dwordx4 v[60:61], v[72:75], off offset:1024 sc1
	s_cbranch_scc1 .LBB0_113
.LBB0_116:
	v_add_u32_e32 v56, s14, v68
	v_cmp_lt_i32_e32 vcc, s3, v56
	s_and_saveexec_b64 s[12:13], vcc
	s_xor_b64 s[12:13], exec, s[12:13]
	v_add_u32_e32 v58, 0xfffff000, v56
	v_mov_b32_e32 v59, v33
	v_lshlrev_b64 v[58:59], 12, v[58:59]
	v_lshl_add_u64 v[58:59], s[38:39], 0, v[58:59]
	v_mov_b32_e32 v57, v33
	s_andn2_saveexec_b64 s[12:13], s[12:13]
	v_ashrrev_i32_e32 v57, 31, v56
	v_lshlrev_b64 v[58:59], 12, v[56:57]
	v_lshl_add_u64 v[58:59], s[36:37], 0, v[58:59]
	s_or_b64 exec, exec, s[12:13]
	v_lshl_add_u64 v[58:59], v[58:59], 0, v[32:33]
	s_cmp_eq_u32 s14, 0
	s_cbranch_scc0 .Lr0pfA_b
	s_waitcnt vmcnt(12)
	v_mov_b32_e32 v72, v100
	v_mov_b32_e32 v73, v101
	v_mov_b32_e32 v74, v102
	v_mov_b32_e32 v75, v103
	v_mov_b32_e32 v76, v104
	v_mov_b32_e32 v77, v105
	v_mov_b32_e32 v78, v106
	v_mov_b32_e32 v79, v107
	v_mov_b32_e32 v80, v108
	v_mov_b32_e32 v81, v109
	v_mov_b32_e32 v82, v110
	v_mov_b32_e32 v83, v111
	v_mov_b32_e32 v84, v112
	v_mov_b32_e32 v85, v113
	v_mov_b32_e32 v86, v114
	v_mov_b32_e32 v87, v115
	s_branch .Lr0pfA_d
.Lr0pfA_b:
	s_waitcnt vmcnt(8)
	v_mov_b32_e32 v72, v170
	v_mov_b32_e32 v73, v171
	v_mov_b32_e32 v74, v172
	v_mov_b32_e32 v75, v173
	v_mov_b32_e32 v76, v174
	v_mov_b32_e32 v77, v175
	v_mov_b32_e32 v78, v176
	v_mov_b32_e32 v79, v177
	v_mov_b32_e32 v80, v178
	v_mov_b32_e32 v81, v179
	v_mov_b32_e32 v82, v180
	v_mov_b32_e32 v83, v181
	v_mov_b32_e32 v84, v182
	v_mov_b32_e32 v85, v183
	v_mov_b32_e32 v86, v184
	v_mov_b32_e32 v87, v185
.Lr0pfA_d:
	s_nop 0
	v_mov_b32_e32 v60, v73
	s_nop 0
	v_mov_b32_e32 v61, v77
	v_mov_b32_e32 v58, v72
	v_mov_b32_e32 v59, v76
	s_nop 0
	v_mov_b32_e32 v94, v81
	s_nop 0
	v_mov_b32_e32 v95, v85
	v_pk_mul_f32 v[60:61], v[60:61], v[60:61]
	v_mov_b32_e32 v88, v74
	v_mov_b32_e32 v89, v78
	v_mov_b32_e32 v92, v80
	v_mov_b32_e32 v93, v84
	v_pk_mul_f32 v[94:95], v[94:95], v[94:95]
	v_pk_fma_f32 v[58:59], v[58:59], v[58:59], v[60:61]
	v_mov_b32_e32 v90, v75
	v_mov_b32_e32 v91, v79
	v_mov_b32_e32 v96, v82
	v_mov_b32_e32 v97, v86
	v_pk_fma_f32 v[60:61], v[92:93], v[92:93], v[94:95]
	v_pk_fma_f32 v[58:59], v[88:89], v[88:89], v[58:59]
	v_mov_b32_e32 v98, v83
	v_mov_b32_e32 v99, v87
	v_pk_fma_f32 v[60:61], v[96:97], v[96:97], v[60:61]
	v_pk_fma_f32 v[58:59], v[90:91], v[90:91], v[58:59]
	v_pk_fma_f32 v[60:61], v[98:99], v[98:99], v[60:61]
	v_add_f32_e32 v58, v58, v59
	v_add_f32_e32 v58, v58, v60
	v_add_f32_e32 v58, v58, v61
	ds_bpermute_b32 v59, v62, v58
	v_lshlrev_b64 v[60:61], 11, v[56:57]
	v_lshl_add_u64 v[60:61], v[34:35], 0, v[60:61]
	s_waitcnt lgkmcnt(0)
	v_add_f32_e32 v58, v58, v59
	ds_bpermute_b32 v59, v63, v58
	s_waitcnt lgkmcnt(0)
	v_add_f32_e32 v58, v58, v59
	ds_bpermute_b32 v59, v64, v58
	s_waitcnt lgkmcnt(0)
	v_add_f32_e32 v58, v58, v59
	ds_bpermute_b32 v59, v65, v58
	s_waitcnt lgkmcnt(0)
	v_add_f32_e32 v58, v58, v59
	ds_bpermute_b32 v59, v66, v58
	s_waitcnt lgkmcnt(0)
	v_add_f32_e32 v58, v58, v59
	ds_bpermute_b32 v59, v67, v58
	s_waitcnt lgkmcnt(0)
	v_add_f32_e32 v58, v58, v59
	v_fmamk_f32 v58, v58, 0x3a800000, v70
	v_mul_f32_e32 v59, 0x4b800000, v58
	v_cmp_gt_f32_e32 vcc, s10, v58
	s_nop 1
	v_cndmask_b32_e32 v58, v58, v59, vcc
	v_rsq_f32_e32 v59, v58
	v_add_u32_e32 v58, 1, v56
	v_mul_f32_e32 v57, 0x45800000, v59
	v_cndmask_b32_e32 v88, v59, v57, vcc
	v_pk_mul_f32 v[74:75], v[74:75], v[88:89] op_sel_hi:[1,0]
	v_pk_mul_f32 v[72:73], v[72:73], v[88:89] op_sel_hi:[1,0]
	v_pk_mul_f32 v[78:79], v[78:79], v[88:89] op_sel_hi:[1,0]
	v_pk_mul_f32 v[76:77], v[76:77], v[88:89] op_sel_hi:[1,0]
	v_pk_mul_f32 v[82:83], v[82:83], v[88:89] op_sel_hi:[1,0]
	v_pk_mul_f32 v[80:81], v[80:81], v[88:89] op_sel_hi:[1,0]
	v_pk_mul_f32 v[86:87], v[86:87], v[88:89] op_sel_hi:[1,0]
	v_pk_mul_f32 v[84:85], v[84:85], v[88:89] op_sel_hi:[1,0]
	v_pk_mul_f32 v[72:73], v[4:5], v[72:73]
	v_pk_mul_f32 v[74:75], v[6:7], v[74:75]
	v_pk_mul_f32 v[76:77], v[0:1], v[76:77]
	v_pk_mul_f32 v[78:79], v[2:3], v[78:79]
	v_pk_mul_f32 v[80:81], v[20:21], v[80:81]
	v_pk_mul_f32 v[82:83], v[22:23], v[82:83]
	v_pk_mul_f32 v[84:85], v[16:17], v[84:85]
	v_pk_mul_f32 v[86:87], v[18:19], v[86:87]
	v_pk_fma_f32 v[74:75], v[40:41], v[74:75], v[14:15]
	v_pk_fma_f32 v[72:73], v[42:43], v[72:73], v[12:13]
	v_pk_fma_f32 v[78:79], v[44:45], v[78:79], v[10:11]
	v_pk_fma_f32 v[76:77], v[46:47], v[76:77], v[8:9]
	v_pk_fma_f32 v[82:83], v[48:49], v[82:83], v[30:31]
	v_pk_fma_f32 v[80:81], v[50:51], v[80:81], v[28:29]
	v_pk_fma_f32 v[86:87], v[52:53], v[86:87], v[26:27]
	v_pk_fma_f32 v[84:85], v[54:55], v[84:85], v[24:25]
	v_cvt_pk_bf16_f32 v72, v72, v73
	v_cvt_pk_bf16_f32 v73, v74, v75
	v_cvt_pk_bf16_f32 v74, v76, v77
	v_cvt_pk_bf16_f32 v75, v78, v79
	v_cmp_lt_i32_e32 vcc, s3, v58
	v_cvt_pk_bf16_f32 v76, v80, v81
	v_cvt_pk_bf16_f32 v77, v82, v83
	v_cvt_pk_bf16_f32 v78, v84, v85
	v_cvt_pk_bf16_f32 v79, v86, v87
	global_store_dwordx4 v[60:61], v[72:75], off sc1
	global_store_dwordx4 v[60:61], v[76:79], off offset:1024 sc1
	s_and_saveexec_b64 s[12:13], vcc
	s_xor_b64 s[12:13], exec, s[12:13]
	v_add_u32_e32 v56, 0xfffff001, v56
	v_mov_b32_e32 v57, v33
	v_lshlrev_b64 v[56:57], 12, v[56:57]
	v_lshl_add_u64 v[60:61], s[38:39], 0, v[56:57]
	v_mov_b32_e32 v59, v33
	s_andn2_saveexec_b64 s[12:13], s[12:13]
	s_cbranch_execz .LBB0_115
	v_ashrrev_i32_e32 v59, 31, v58
	v_lshlrev_b64 v[56:57], 12, v[58:59]
	v_lshl_add_u64 v[60:61], s[36:37], 0, v[56:57]
	s_branch .LBB0_115

.LBB0_863:
	v_lshl_add_u32 v0, v105, 2, v103
	v_ashrrev_i32_e32 v0, 11, v0
	v_add_u32_e32 v0, 1, v0
	v_cmp_lt_i32_e32 vcc, s2, v105
	s_mov_b32 s5, 0
	s_nop 0
	v_cndmask_b32_e32 v2, 0, v0, vcc
	v_mul_hi_i32_i24_e32 v1, 0x6000, v2
	v_mul_i32_i24_e32 v0, 0x6000, v2
	v_lshl_add_u64 v[0:1], s[56:57], 0, v[0:1]
	v_add_u32_e32 v2, 3, v2
	v_mul_hi_i32_i24_e32 v3, 0x6000, v2
	v_mul_i32_i24_e32 v2, 0x6000, v2
	v_lshl_add_u64 v[40:41], v[0:1], 0, s[12:13]
	v_lshl_add_u64 v[24:25], s[56:57], 0, v[2:3]
	v_lshl_add_u64 v[12:13], v[40:41], 0, v[64:65]
	v_lshl_add_u64 v[48:49], v[24:25], 0, s[14:15]
	global_load_dwordx4 v[0:3], v[72:73], off offset:16
	global_load_dwordx4 v[4:7], v[72:73], off
	global_load_dwordx4 v[8:11], v[12:13], off offset:16
	s_nop 0
	global_load_dwordx4 v[12:15], v[12:13], off
	s_nop 0
	global_load_dwordx4 v[16:19], v[74:75], off offset:16
	global_load_dwordx4 v[20:23], v[74:75], off
	v_lshl_add_u64 v[60:61], v[24:25], 0, v[64:65]
	v_lshl_add_u64 v[32:33], v[48:49], 0, v[64:65]
	v_lshl_add_u64 v[44:45], v[40:41], 0, v[80:81]
	global_load_dwordx4 v[24:27], v[60:61], off offset:16
	global_load_dwordx4 v[28:31], v[60:61], off
	global_load_dwordx4 v[88:91], v[32:33], off offset:16
	global_load_dwordx4 v[84:87], v[32:33], off
	s_nop 0
	global_load_dwordx4 v[32:35], v[76:77], off offset:16
	global_load_dwordx4 v[36:39], v[76:77], off
	global_load_dwordx4 v[40:43], v[44:45], off offset:16
	s_nop 0
	global_load_dwordx4 v[44:47], v[44:45], off
	v_lshl_add_u64 v[48:49], v[48:49], 0, v[80:81]
	global_load_dwordx4 v[96:99], v[48:49], off offset:16
	global_load_dwordx4 v[92:95], v[48:49], off
	s_nop 0
	global_load_dwordx4 v[48:51], v[78:79], off offset:16
	global_load_dwordx4 v[52:55], v[78:79], off
	global_load_dwordx4 v[56:59], v[60:61], off offset:2064
	s_nop 0
	global_load_dwordx4 v[60:63], v[60:61], off offset:2048
	s_waitcnt vmcnt(11)
	v_pk_add_f32 v[88:89], v[88:89], 1.0 op_sel_hi:[1,0]
	s_waitcnt vmcnt(10)
	v_pk_add_f32 v[82:83], v[86:87], 1.0 op_sel_hi:[1,0]
	v_pk_add_f32 v[84:85], v[84:85], 1.0 op_sel_hi:[1,0]
	v_pk_add_f32 v[86:87], v[90:91], 1.0 op_sel_hi:[1,0]
	s_waitcnt vmcnt(4)
	v_pk_add_f32 v[90:91], v[94:95], 1.0 op_sel_hi:[1,0]
	v_pk_add_f32 v[92:93], v[92:93], 1.0 op_sel_hi:[1,0]
	v_pk_add_f32 v[94:95], v[98:99], 1.0 op_sel_hi:[1,0]
	v_pk_add_f32 v[96:97], v[96:97], 1.0 op_sel_hi:[1,0]
	v_mov_b32_e32 v98, v102
	v_ashrrev_i32_e32 v99, 31, v102
	s_mov_b64 s[60:61], 0x1000
	v_lshlrev_b64 v[98:99], 11, v[98:99]
	v_lshl_add_u64 v[122:123], v[66:67], 0, v[98:99]
	v_lshl_add_u64 v[118:119], v[68:69], 0, v[98:99]
	global_load_dwordx4 v[224:227], v[122:123], off
	global_load_dwordx4 v[228:231], v[122:123], off offset:1024
	global_load_dwordx4 v[232:235], v[118:119], off
	global_load_dwordx4 v[236:239], v[118:119], off offset:1024
	global_load_dwordx4 v[240:243], v[122:123], off offset:2048
	global_load_dwordx4 v[244:247], v[122:123], off offset:3072
	global_load_dwordx4 v[248:251], v[118:119], off offset:2048
	global_load_dwordx4 v[252:255], v[118:119], off offset:3072
	v_lshl_add_u64 v[122:123], v[122:123], 0, s[60:61]
	v_lshl_add_u64 v[118:119], v[118:119], 0, s[60:61]
	global_load_dwordx4 v[188:191], v[122:123], off
	global_load_dwordx4 v[192:195], v[122:123], off offset:1024
	global_load_dwordx4 v[196:199], v[118:119], off
	global_load_dwordx4 v[200:203], v[118:119], off offset:1024
	global_load_dwordx4 v[204:207], v[122:123], off offset:2048
	global_load_dwordx4 v[208:211], v[122:123], off offset:3072
	global_load_dwordx4 v[212:215], v[118:119], off offset:2048
	global_load_dwordx4 v[220:223], v[118:119], off offset:3072
.LBB0_864:
	v_add_u32_e32 v98, s5, v102
	v_ashrrev_i32_e32 v99, 31, v98
	v_add_u32_e32 v100, 1, v98
	v_lshlrev_b64 v[98:99], 11, v[98:99]
	v_lshl_add_u64 v[122:123], v[66:67], 0, v[98:99]
	v_lshl_add_u64 v[118:119], v[68:69], 0, v[98:99]
	s_cmp_eq_u32 s5, 0
	s_cbranch_scc0 .Lrpfr20A_b
	s_waitcnt vmcnt(12)
	v_mov_b32_e32 v106, v224
	v_mov_b32_e32 v107, v225
	v_mov_b32_e32 v108, v226
	v_mov_b32_e32 v109, v227
	v_mov_b32_e32 v110, v228
	v_mov_b32_e32 v111, v229
	v_mov_b32_e32 v112, v230
	v_mov_b32_e32 v113, v231
	v_mov_b32_e32 v114, v232
	v_mov_b32_e32 v115, v233
	v_mov_b32_e32 v116, v234
	v_mov_b32_e32 v117, v235
	v_mov_b32_e32 v118, v236
	v_mov_b32_e32 v119, v237
	v_mov_b32_e32 v120, v238
	v_mov_b32_e32 v121, v239
	s_branch .Lrpfr20A_d
.Lrpfr20A_b:
	s_waitcnt vmcnt(12)
	v_mov_b32_e32 v106, v188
	v_mov_b32_e32 v107, v189
	v_mov_b32_e32 v108, v190
	v_mov_b32_e32 v109, v191
	v_mov_b32_e32 v110, v192
	v_mov_b32_e32 v111, v193
	v_mov_b32_e32 v112, v194
	v_mov_b32_e32 v113, v195
	v_mov_b32_e32 v114, v196
	v_mov_b32_e32 v115, v197
	v_mov_b32_e32 v116, v198
	v_mov_b32_e32 v117, v199
	v_mov_b32_e32 v118, v200
	v_mov_b32_e32 v119, v201
	v_mov_b32_e32 v120, v202
	v_mov_b32_e32 v121, v203
.Lrpfr20A_d:
	s_nop 0
	v_ashrrev_i32_e32 v101, 31, v100
	v_lshl_add_u64 v[124:125], v[70:71], 0, v[98:99]
	v_lshlrev_b64 v[98:99], 11, v[100:101]
	v_lshl_add_u64 v[100:101], v[66:67], 0, v[98:99]
	v_lshl_add_u64 v[126:127], v[68:69], 0, v[98:99]
	s_add_i32 s5, s5, 2
	s_cmp_eq_u32 s5, 4
	v_lshl_add_u64 v[98:99], v[70:71], 0, v[98:99]
	s_nop 0
	v_lshlrev_b32_e32 v128, 16, v106
	v_and_b32_e32 v129, 0xffff0000, v106
	s_nop 0
	v_and_b32_e32 v139, 0xffff0000, v116
	v_and_b32_e32 v138, 0xffff0000, v114
	v_lshlrev_b32_e32 v137, 16, v116
	v_lshlrev_b32_e32 v136, 16, v114
	v_lshlrev_b32_e32 v140, 16, v115
	v_and_b32_e32 v116, 0xffff0000, v115
	s_nop 0
	v_lshlrev_b32_e32 v115, 16, v118
	v_lshlrev_b32_e32 v114, 16, v120
	v_and_b32_e32 v143, 0xffff0000, v118
	v_and_b32_e32 v142, 0xffff0000, v120
	v_lshlrev_b32_e32 v150, 16, v121
	v_and_b32_e32 v118, 0xffff0000, v121
	v_pk_mul_f32 v[120:121], v[138:139], v[138:139]
	v_lshlrev_b32_e32 v141, 16, v117
	v_pk_mul_f32 v[152:153], v[142:143], v[142:143]
	v_pk_fma_f32 v[120:121], v[136:137], v[136:137], v[120:121]
	v_and_b32_e32 v117, 0xffff0000, v117
	v_lshlrev_b32_e32 v151, 16, v119
	v_mov_b32_e32 v156, v136
	v_mov_b32_e32 v157, v138
	v_mov_b32_e32 v138, v137
	v_pk_fma_f32 v[136:137], v[114:115], v[114:115], v[152:153]
	v_pk_fma_f32 v[120:121], v[140:141], v[140:141], v[120:121]
	v_and_b32_e32 v119, 0xffff0000, v119
	v_pk_fma_f32 v[136:137], v[150:151], v[150:151], v[136:137]
	v_pk_fma_f32 v[120:121], v[116:117], v[116:117], v[120:121]
	v_mov_b32_e32 v158, v151
	v_mov_b32_e32 v159, v119
	v_mov_b32_e32 v151, v118
	v_pk_fma_f32 v[118:119], v[118:119], v[118:119], v[136:137]
	v_add_f32_e32 v120, v120, v121
	v_add_f32_e32 v119, v120, v119
	v_add_f32_e32 v118, v118, v119
	ds_bpermute_b32 v119, v172, v118
	v_mov_b32_e32 v154, v140
	v_mov_b32_e32 v155, v116
	v_mov_b32_e32 v116, v141
	v_mov_b32_e32 v186, v115
	s_waitcnt lgkmcnt(0)
	v_add_f32_e32 v118, v118, v119
	ds_bpermute_b32 v119, v173, v118
	v_mov_b32_e32 v187, v143
	v_mov_b32_e32 v115, v142
	v_lshlrev_b32_e32 v106, 16, v107
	v_and_b32_e32 v107, 0xffff0000, v107
	s_waitcnt lgkmcnt(0)
	v_add_f32_e32 v118, v118, v119
	ds_bpermute_b32 v119, v174, v118
	v_lshlrev_b32_e32 v130, 16, v108
	v_and_b32_e32 v131, 0xffff0000, v108
	v_lshlrev_b32_e32 v108, 16, v109
	v_and_b32_e32 v109, 0xffff0000, v109
	s_waitcnt lgkmcnt(0)
	v_add_f32_e32 v118, v118, v119
	ds_bpermute_b32 v119, v175, v118
	v_lshlrev_b32_e32 v132, 16, v110
	v_and_b32_e32 v133, 0xffff0000, v110
	v_lshlrev_b32_e32 v110, 16, v111
	v_and_b32_e32 v111, 0xffff0000, v111
	s_waitcnt lgkmcnt(0)
	v_add_f32_e32 v118, v118, v119
	ds_bpermute_b32 v119, v176, v118
	v_lshlrev_b32_e32 v134, 16, v112
	v_and_b32_e32 v135, 0xffff0000, v112
	v_lshlrev_b32_e32 v112, 16, v113
	v_and_b32_e32 v113, 0xffff0000, v113
	s_waitcnt lgkmcnt(0)
	v_add_f32_e32 v118, v118, v119
	ds_bpermute_b32 v119, v177, v118
	s_waitcnt lgkmcnt(0)
	v_add_f32_e32 v118, v118, v119
	v_fmamk_f32 v118, v118, 0x3a800000, v104
	v_mul_f32_e32 v119, 0x4b800000, v118
	v_cmp_gt_f32_e32 vcc, s3, v118
	s_nop 1
	v_cndmask_b32_e32 v118, v118, v119, vcc
	v_rsq_f32_e32 v118, v118
	s_nop 0
	v_mul_f32_e32 v119, 0x45800000, v118
	v_cndmask_b32_e32 v118, v118, v119, vcc
	v_pk_mul_f32 v[120:121], v[118:119], v[154:155] op_sel_hi:[0,1]
	v_pk_mul_f32 v[136:137], v[118:119], v[156:157] op_sel_hi:[0,1]
	v_pk_mul_f32 v[116:117], v[118:119], v[116:117] op_sel_hi:[0,1]
	v_pk_mul_f32 v[138:139], v[118:119], v[138:139] op_sel_hi:[0,1]
	v_pk_mul_f32 v[140:141], v[118:119], v[158:159] op_sel_hi:[0,1]
	v_pk_mul_f32 v[142:143], v[118:119], v[186:187] op_sel_hi:[0,1]
	v_pk_mul_f32 v[150:151], v[118:119], v[150:151] op_sel_hi:[0,1]
	v_pk_mul_f32 v[114:115], v[118:119], v[114:115] op_sel_hi:[0,1]
	v_pk_mul_f32 v[118:119], v[4:5], v[136:137]
	v_pk_mul_f32 v[120:121], v[6:7], v[120:121]
	v_pk_mul_f32 v[136:137], v[0:1], v[138:139]
	v_pk_mul_f32 v[116:117], v[2:3], v[116:117]
	v_pk_mul_f32 v[138:139], v[36:37], v[142:143]
	v_pk_mul_f32 v[140:141], v[38:39], v[140:141]
	v_pk_mul_f32 v[114:115], v[32:33], v[114:115]
	v_pk_mul_f32 v[142:143], v[34:35], v[150:151]
	v_pk_fma_f32 v[120:121], v[14:15], v[120:121], v[106:107]
	v_pk_fma_f32 v[118:119], v[12:13], v[118:119], v[128:129]
	v_pk_fma_f32 v[116:117], v[10:11], v[116:117], v[108:109]
	v_pk_fma_f32 v[128:129], v[8:9], v[136:137], v[130:131]
	v_pk_fma_f32 v[130:131], v[46:47], v[140:141], v[110:111]
	v_pk_fma_f32 v[132:133], v[44:45], v[138:139], v[132:133]
	v_pk_fma_f32 v[136:137], v[42:43], v[142:143], v[112:113]
	v_pk_fma_f32 v[114:115], v[40:41], v[114:115], v[134:135]
	v_cvt_pk_bf16_f32 v106, v118, v119
	v_cvt_pk_bf16_f32 v107, v120, v121
	v_cvt_pk_bf16_f32 v108, v128, v129
	v_cvt_pk_bf16_f32 v109, v116, v117
	v_mov_b32_e32 v138, v119
	v_mov_b32_e32 v139, v129
	v_cvt_pk_bf16_f32 v110, v132, v133
	v_cvt_pk_bf16_f32 v111, v130, v131
	v_cvt_pk_bf16_f32 v112, v114, v115
	v_cvt_pk_bf16_f32 v113, v136, v137
	v_mov_b32_e32 v134, v118
	v_mov_b32_e32 v135, v128
	v_mov_b32_e32 v152, v115
	v_mov_b32_e32 v153, v133
	global_store_dwordx4 v[122:123], v[106:109], off sc1
	global_store_dwordx4 v[122:123], v[110:113], off offset:1024 sc1
	v_mov_b32_e32 v140, v120
	v_pk_mul_f32 v[106:107], v[138:139], v[138:139]
	v_mov_b32_e32 v141, v116
	v_mov_b32_e32 v150, v114
	v_mov_b32_e32 v151, v132
	v_pk_mul_f32 v[108:109], v[152:153], v[152:153]
	v_pk_fma_f32 v[106:107], v[134:135], v[134:135], v[106:107]
	v_mov_b32_e32 v142, v121
	v_mov_b32_e32 v143, v117
	v_mov_b32_e32 v154, v136
	v_mov_b32_e32 v155, v130
	v_pk_fma_f32 v[108:109], v[150:151], v[150:151], v[108:109]
	v_pk_fma_f32 v[106:107], v[140:141], v[140:141], v[106:107]
	v_mov_b32_e32 v156, v137
	v_mov_b32_e32 v157, v131
	v_pk_fma_f32 v[108:109], v[154:155], v[154:155], v[108:109]
	v_pk_fma_f32 v[106:107], v[142:143], v[142:143], v[106:107]
	v_pk_fma_f32 v[108:109], v[156:157], v[156:157], v[108:109]
	v_add_f32_e32 v106, v106, v107
	v_add_f32_e32 v106, v109, v106
	v_add_f32_e32 v106, v108, v106
	ds_bpermute_b32 v107, v172, v106
	s_waitcnt lgkmcnt(0)
	v_add_f32_e32 v106, v106, v107
	ds_bpermute_b32 v107, v173, v106
	s_waitcnt lgkmcnt(0)
	v_add_f32_e32 v106, v106, v107
	ds_bpermute_b32 v107, v174, v106
	s_waitcnt lgkmcnt(0)
	v_add_f32_e32 v106, v106, v107
	ds_bpermute_b32 v107, v175, v106
	s_waitcnt lgkmcnt(0)
	v_add_f32_e32 v106, v106, v107
	ds_bpermute_b32 v107, v176, v106
	s_waitcnt lgkmcnt(0)
	v_add_f32_e32 v106, v106, v107
	ds_bpermute_b32 v107, v177, v106
	s_waitcnt lgkmcnt(0)
	v_add_f32_e32 v106, v106, v107
	v_fmamk_f32 v106, v106, 0x3a800000, v104
	v_mul_f32_e32 v107, 0x4b800000, v106
	v_cmp_gt_f32_e32 vcc, s3, v106
	s_nop 1
	v_cndmask_b32_e32 v106, v106, v107, vcc
	v_rsq_f32_e32 v106, v106
	s_nop 0
	v_mul_f32_e32 v107, 0x45800000, v106
	v_cndmask_b32_e32 v106, v106, v107, vcc
	v_pk_mul_f32 v[108:109], v[120:121], v[106:107] op_sel_hi:[1,0]
	v_pk_mul_f32 v[110:111], v[118:119], v[106:107] op_sel_hi:[1,0]
	v_pk_mul_f32 v[112:113], v[116:117], v[106:107] op_sel_hi:[1,0]
	v_pk_mul_f32 v[116:117], v[128:129], v[106:107] op_sel_hi:[1,0]
	v_pk_mul_f32 v[118:119], v[130:131], v[106:107] op_sel_hi:[1,0]
	v_pk_mul_f32 v[120:121], v[132:133], v[106:107] op_sel_hi:[1,0]
	v_pk_mul_f32 v[122:123], v[136:137], v[106:107] op_sel_hi:[1,0]
	v_pk_mul_f32 v[106:107], v[114:115], v[106:107] op_sel_hi:[1,0]
	v_pk_mul_f32 v[110:111], v[20:21], v[110:111]
	v_pk_mul_f32 v[108:109], v[22:23], v[108:109]
	v_pk_mul_f32 v[114:115], v[16:17], v[116:117]
	v_pk_mul_f32 v[112:113], v[18:19], v[112:113]
	v_pk_mul_f32 v[116:117], v[52:53], v[120:121]
	v_pk_mul_f32 v[118:119], v[54:55], v[118:119]
	v_pk_mul_f32 v[106:107], v[48:49], v[106:107]
	v_pk_mul_f32 v[120:121], v[50:51], v[122:123]
	v_pk_fma_f32 v[108:109], v[82:83], v[108:109], v[30:31]
	v_pk_fma_f32 v[110:111], v[84:85], v[110:111], v[28:29]
	v_pk_fma_f32 v[112:113], v[86:87], v[112:113], v[26:27]
	v_pk_fma_f32 v[114:115], v[88:89], v[114:115], v[24:25]
	v_pk_fma_f32 v[118:119], v[90:91], v[118:119], v[62:63]
	v_pk_fma_f32 v[116:117], v[92:93], v[116:117], v[60:61]
	v_pk_fma_f32 v[120:121], v[94:95], v[120:121], v[58:59]
	v_pk_fma_f32 v[122:123], v[96:97], v[106:107], v[56:57]
	v_cvt_pk_bf16_f32 v106, v110, v111
	v_cvt_pk_bf16_f32 v107, v108, v109
	v_cvt_pk_bf16_f32 v108, v114, v115
	v_cvt_pk_bf16_f32 v109, v112, v113
	v_cvt_pk_bf16_f32 v110, v116, v117
	v_cvt_pk_bf16_f32 v111, v118, v119
	v_cvt_pk_bf16_f32 v112, v122, v123
	v_cvt_pk_bf16_f32 v113, v120, v121
	global_store_dwordx4 v[124:125], v[106:109], off sc1
	global_store_dwordx4 v[124:125], v[110:113], off offset:1024 sc1
	s_cselect_b32 s62, 1, 0
	s_cmp_eq_u32 s5, 2
	s_cbranch_scc0 .Lrpfr20B_b
	s_waitcnt vmcnt(12)
	v_mov_b32_e32 v106, v240
	v_mov_b32_e32 v107, v241
	v_mov_b32_e32 v108, v242
	v_mov_b32_e32 v109, v243
	v_mov_b32_e32 v110, v244
	v_mov_b32_e32 v111, v245
	v_mov_b32_e32 v112, v246
	v_mov_b32_e32 v113, v247
	v_mov_b32_e32 v114, v248
	v_mov_b32_e32 v115, v249
	v_mov_b32_e32 v116, v250
	v_mov_b32_e32 v117, v251
	v_mov_b32_e32 v118, v252
	v_mov_b32_e32 v119, v253
	v_mov_b32_e32 v120, v254
	v_mov_b32_e32 v121, v255
	s_branch .Lrpfr20B_d
.Lrpfr20B_b:
	s_waitcnt vmcnt(12)
	v_mov_b32_e32 v106, v204
	v_mov_b32_e32 v107, v205
	v_mov_b32_e32 v108, v206
	v_mov_b32_e32 v109, v207
	v_mov_b32_e32 v110, v208
	v_mov_b32_e32 v111, v209
	v_mov_b32_e32 v112, v210
	v_mov_b32_e32 v113, v211
	v_mov_b32_e32 v114, v212
	v_mov_b32_e32 v115, v213
	v_mov_b32_e32 v116, v214
	v_mov_b32_e32 v117, v215
	v_mov_b32_e32 v118, v220
	v_mov_b32_e32 v119, v221
	v_mov_b32_e32 v120, v222
	v_mov_b32_e32 v121, v223
.Lrpfr20B_d:
	s_cmp_lg_u32 s62, 0
	s_nop 0
	s_nop 0
	v_lshlrev_b32_e32 v122, 16, v106
	v_and_b32_e32 v123, 0xffff0000, v106
	s_nop 0
	v_and_b32_e32 v133, 0xffff0000, v116
	v_and_b32_e32 v132, 0xffff0000, v114
	v_lshlrev_b32_e32 v131, 16, v116
	v_lshlrev_b32_e32 v130, 16, v114
	v_lshlrev_b32_e32 v134, 16, v115
	v_and_b32_e32 v116, 0xffff0000, v115
	s_nop 0
	v_lshlrev_b32_e32 v115, 16, v118
	v_lshlrev_b32_e32 v114, 16, v120
	v_and_b32_e32 v137, 0xffff0000, v118
	v_and_b32_e32 v136, 0xffff0000, v120
	v_lshlrev_b32_e32 v138, 16, v121
	v_and_b32_e32 v118, 0xffff0000, v121
	v_pk_mul_f32 v[120:121], v[132:133], v[132:133]
	v_lshlrev_b32_e32 v135, 16, v117
	v_pk_mul_f32 v[140:141], v[136:137], v[136:137]
	v_pk_fma_f32 v[120:121], v[130:131], v[130:131], v[120:121]
	v_and_b32_e32 v117, 0xffff0000, v117
	v_lshlrev_b32_e32 v139, 16, v119
	v_mov_b32_e32 v150, v130
	v_mov_b32_e32 v151, v132
	v_mov_b32_e32 v132, v131
	v_pk_fma_f32 v[130:131], v[114:115], v[114:115], v[140:141]
	v_pk_fma_f32 v[120:121], v[134:135], v[134:135], v[120:121]
	v_and_b32_e32 v119, 0xffff0000, v119
	v_pk_fma_f32 v[130:131], v[138:139], v[138:139], v[130:131]
	v_pk_fma_f32 v[120:121], v[116:117], v[116:117], v[120:121]
	v_mov_b32_e32 v152, v139
	v_mov_b32_e32 v153, v119
	v_mov_b32_e32 v139, v118
	v_pk_fma_f32 v[118:119], v[118:119], v[118:119], v[130:131]
	v_add_f32_e32 v120, v120, v121
	v_add_f32_e32 v119, v120, v119
	v_add_f32_e32 v118, v118, v119
	ds_bpermute_b32 v119, v172, v118
	v_mov_b32_e32 v142, v134
	v_mov_b32_e32 v143, v116
	v_mov_b32_e32 v116, v135
	v_mov_b32_e32 v154, v115
	s_waitcnt lgkmcnt(0)
	v_add_f32_e32 v118, v118, v119
	ds_bpermute_b32 v119, v173, v118
	v_mov_b32_e32 v155, v137
	v_mov_b32_e32 v115, v136
	v_lshlrev_b32_e32 v106, 16, v107
	v_and_b32_e32 v107, 0xffff0000, v107
	s_waitcnt lgkmcnt(0)
	v_add_f32_e32 v118, v118, v119
	ds_bpermute_b32 v119, v174, v118
	v_lshlrev_b32_e32 v124, 16, v108
	v_and_b32_e32 v125, 0xffff0000, v108
	v_lshlrev_b32_e32 v108, 16, v109
	v_and_b32_e32 v109, 0xffff0000, v109
	s_waitcnt lgkmcnt(0)
	v_add_f32_e32 v118, v118, v119
	ds_bpermute_b32 v119, v175, v118
	v_lshlrev_b32_e32 v126, 16, v110
	v_and_b32_e32 v127, 0xffff0000, v110
	v_lshlrev_b32_e32 v110, 16, v111
	v_and_b32_e32 v111, 0xffff0000, v111
	s_waitcnt lgkmcnt(0)
	v_add_f32_e32 v118, v118, v119
	ds_bpermute_b32 v119, v176, v118
	v_lshlrev_b32_e32 v128, 16, v112
	v_and_b32_e32 v129, 0xffff0000, v112
	v_lshlrev_b32_e32 v112, 16, v113
	v_and_b32_e32 v113, 0xffff0000, v113
	s_waitcnt lgkmcnt(0)
	v_add_f32_e32 v118, v118, v119
	ds_bpermute_b32 v119, v177, v118
	s_waitcnt lgkmcnt(0)
	v_add_f32_e32 v118, v118, v119
	v_fmamk_f32 v118, v118, 0x3a800000, v104
	v_mul_f32_e32 v119, 0x4b800000, v118
	v_cmp_gt_f32_e32 vcc, s3, v118
	s_nop 1
	v_cndmask_b32_e32 v118, v118, v119, vcc
	v_rsq_f32_e32 v118, v118
	s_nop 0
	v_mul_f32_e32 v119, 0x45800000, v118
	v_cndmask_b32_e32 v118, v118, v119, vcc
	v_pk_mul_f32 v[120:121], v[118:119], v[142:143] op_sel_hi:[0,1]
	v_pk_mul_f32 v[130:131], v[118:119], v[150:151] op_sel_hi:[0,1]
	v_pk_mul_f32 v[116:117], v[118:119], v[116:117] op_sel_hi:[0,1]
	v_pk_mul_f32 v[132:133], v[118:119], v[132:133] op_sel_hi:[0,1]
	v_pk_mul_f32 v[134:135], v[118:119], v[152:153] op_sel_hi:[0,1]
	v_pk_mul_f32 v[136:137], v[118:119], v[154:155] op_sel_hi:[0,1]
	v_pk_mul_f32 v[138:139], v[118:119], v[138:139] op_sel_hi:[0,1]
	v_pk_mul_f32 v[114:115], v[118:119], v[114:115] op_sel_hi:[0,1]
	v_pk_mul_f32 v[118:119], v[4:5], v[130:131]
	v_pk_mul_f32 v[120:121], v[6:7], v[120:121]
	v_pk_mul_f32 v[130:131], v[0:1], v[132:133]
	v_pk_mul_f32 v[116:117], v[2:3], v[116:117]
	v_pk_mul_f32 v[132:133], v[36:37], v[136:137]
	v_pk_mul_f32 v[134:135], v[38:39], v[134:135]
	v_pk_mul_f32 v[114:115], v[32:33], v[114:115]
	v_pk_mul_f32 v[136:137], v[34:35], v[138:139]
	v_pk_fma_f32 v[120:121], v[14:15], v[120:121], v[106:107]
	v_pk_fma_f32 v[118:119], v[12:13], v[118:119], v[122:123]
	v_pk_fma_f32 v[116:117], v[10:11], v[116:117], v[108:109]
	v_pk_fma_f32 v[122:123], v[8:9], v[130:131], v[124:125]
	v_pk_fma_f32 v[124:125], v[46:47], v[134:135], v[110:111]
	v_pk_fma_f32 v[126:127], v[44:45], v[132:133], v[126:127]
	v_pk_fma_f32 v[130:131], v[42:43], v[136:137], v[112:113]
	v_pk_fma_f32 v[114:115], v[40:41], v[114:115], v[128:129]
	v_cvt_pk_bf16_f32 v106, v118, v119
	v_cvt_pk_bf16_f32 v107, v120, v121
	v_cvt_pk_bf16_f32 v108, v122, v123
	v_cvt_pk_bf16_f32 v109, v116, v117
	v_mov_b32_e32 v132, v119
	v_mov_b32_e32 v133, v123
	v_cvt_pk_bf16_f32 v110, v126, v127
	v_cvt_pk_bf16_f32 v111, v124, v125
	v_cvt_pk_bf16_f32 v112, v114, v115
	v_cvt_pk_bf16_f32 v113, v130, v131
	v_mov_b32_e32 v128, v118
	v_mov_b32_e32 v129, v122
	v_mov_b32_e32 v140, v115
	v_mov_b32_e32 v141, v127
	global_store_dwordx4 v[100:101], v[106:109], off sc1
	global_store_dwordx4 v[100:101], v[110:113], off offset:1024 sc1
	v_pk_mul_f32 v[100:101], v[132:133], v[132:133]
	v_mov_b32_e32 v134, v120
	v_mov_b32_e32 v135, v116
	v_mov_b32_e32 v138, v114
	v_mov_b32_e32 v139, v126
	v_pk_mul_f32 v[106:107], v[140:141], v[140:141]
	v_pk_fma_f32 v[100:101], v[128:129], v[128:129], v[100:101]
	v_mov_b32_e32 v136, v121
	v_mov_b32_e32 v137, v117
	v_mov_b32_e32 v142, v130
	v_mov_b32_e32 v143, v124
	v_pk_fma_f32 v[106:107], v[138:139], v[138:139], v[106:107]
	v_pk_fma_f32 v[100:101], v[134:135], v[134:135], v[100:101]
	v_mov_b32_e32 v150, v131
	v_mov_b32_e32 v151, v125
	v_pk_fma_f32 v[106:107], v[142:143], v[142:143], v[106:107]
	v_pk_fma_f32 v[100:101], v[136:137], v[136:137], v[100:101]
	v_pk_fma_f32 v[106:107], v[150:151], v[150:151], v[106:107]
	v_add_f32_e32 v100, v100, v101
	v_add_f32_e32 v100, v107, v100
	v_add_f32_e32 v100, v106, v100
	ds_bpermute_b32 v101, v172, v100
	s_waitcnt lgkmcnt(0)
	v_add_f32_e32 v100, v100, v101
	ds_bpermute_b32 v101, v173, v100
	s_waitcnt lgkmcnt(0)
	v_add_f32_e32 v100, v100, v101
	ds_bpermute_b32 v101, v174, v100
	s_waitcnt lgkmcnt(0)
	v_add_f32_e32 v100, v100, v101
	ds_bpermute_b32 v101, v175, v100
	s_waitcnt lgkmcnt(0)
	v_add_f32_e32 v100, v100, v101
	ds_bpermute_b32 v101, v176, v100
	s_waitcnt lgkmcnt(0)
	v_add_f32_e32 v100, v100, v101
	ds_bpermute_b32 v101, v177, v100
	s_waitcnt lgkmcnt(0)
	v_add_f32_e32 v100, v100, v101
	v_fmamk_f32 v100, v100, 0x3a800000, v104
	v_mul_f32_e32 v101, 0x4b800000, v100
	v_cmp_gt_f32_e32 vcc, s3, v100
	s_nop 1
	v_cndmask_b32_e32 v100, v100, v101, vcc
	v_rsq_f32_e32 v100, v100
	s_nop 0
	v_mul_f32_e32 v101, 0x45800000, v100
	v_cndmask_b32_e32 v100, v100, v101, vcc
	v_pk_mul_f32 v[106:107], v[120:121], v[100:101] op_sel_hi:[1,0]
	v_pk_mul_f32 v[108:109], v[118:119], v[100:101] op_sel_hi:[1,0]
	v_pk_mul_f32 v[110:111], v[116:117], v[100:101] op_sel_hi:[1,0]
	v_pk_mul_f32 v[112:113], v[122:123], v[100:101] op_sel_hi:[1,0]
	v_pk_mul_f32 v[116:117], v[124:125], v[100:101] op_sel_hi:[1,0]
	v_pk_mul_f32 v[118:119], v[126:127], v[100:101] op_sel_hi:[1,0]
	v_pk_mul_f32 v[120:121], v[130:131], v[100:101] op_sel_hi:[1,0]
	v_pk_mul_f32 v[100:101], v[114:115], v[100:101] op_sel_hi:[1,0]
	v_pk_mul_f32 v[108:109], v[20:21], v[108:109]
	v_pk_mul_f32 v[106:107], v[22:23], v[106:107]
	v_pk_mul_f32 v[112:113], v[16:17], v[112:113]
	v_pk_mul_f32 v[110:111], v[18:19], v[110:111]
	v_pk_mul_f32 v[114:115], v[52:53], v[118:119]
	v_pk_mul_f32 v[116:117], v[54:55], v[116:117]
	v_pk_mul_f32 v[100:101], v[48:49], v[100:101]
	v_pk_mul_f32 v[118:119], v[50:51], v[120:121]
	v_pk_fma_f32 v[120:121], v[82:83], v[106:107], v[30:31]
	v_pk_fma_f32 v[106:107], v[84:85], v[108:109], v[28:29]
	v_pk_fma_f32 v[110:111], v[86:87], v[110:111], v[26:27]
	v_pk_fma_f32 v[108:109], v[88:89], v[112:113], v[24:25]
	v_pk_fma_f32 v[112:113], v[90:91], v[116:117], v[62:63]
	v_pk_fma_f32 v[114:115], v[92:93], v[114:115], v[60:61]
	v_pk_fma_f32 v[116:117], v[94:95], v[118:119], v[58:59]
	v_pk_fma_f32 v[100:101], v[96:97], v[100:101], v[56:57]
	v_cvt_pk_bf16_f32 v106, v106, v107
	v_cvt_pk_bf16_f32 v107, v120, v121
	v_cvt_pk_bf16_f32 v108, v108, v109
	v_cvt_pk_bf16_f32 v109, v110, v111
	v_cvt_pk_bf16_f32 v110, v114, v115
	v_cvt_pk_bf16_f32 v111, v112, v113
	v_cvt_pk_bf16_f32 v112, v100, v101
	v_cvt_pk_bf16_f32 v113, v116, v117
	global_store_dwordx4 v[98:99], v[106:109], off sc1
	global_store_dwordx4 v[98:99], v[110:113], off offset:1024 sc1
	s_cbranch_scc0 .LBB0_864
	v_add_u32_e32 v105, s0, v105
	v_cmp_lt_i32_e32 vcc, s4, v105
	s_or_b64 s[8:9], vcc, s[8:9]
	v_add_u32_e32 v102, s1, v102
	s_andn2_b64 exec, exec, s[8:9]
	s_cbranch_execnz .LBB0_863

.LBB0_1290:
	v_lshl_add_u32 v0, v105, 2, v103
	v_ashrrev_i32_e32 v0, 11, v0
	v_add_u32_e32 v0, 4, v0
	v_cmp_lt_i32_e32 vcc, s2, v105
	s_mov_b32 s5, 0
	s_nop 0
	v_cndmask_b32_e32 v0, 3, v0, vcc
	v_mul_hi_i32_i24_e32 v1, 0x6000, v0
	v_mul_i32_i24_e32 v0, 0x6000, v0
	v_lshl_add_u64 v[0:1], s[56:57], 0, v[0:1]
	v_lshl_add_u64 v[40:41], v[0:1], 0, s[12:13]
	v_lshl_add_u64 v[24:25], v[40:41], 0, v[64:65]
	v_lshl_add_u64 v[56:57], v[0:1], 0, s[14:15]
	v_lshl_add_u64 v[48:49], v[0:1], 0, s[18:19]
	global_load_dwordx4 v[0:3], v[72:73], off offset:16
	global_load_dwordx4 v[4:7], v[72:73], off
	global_load_dwordx4 v[8:11], v[24:25], off offset:16
	global_load_dwordx4 v[12:15], v[24:25], off
	global_load_dwordx4 v[16:19], v[74:75], off offset:16
	global_load_dwordx4 v[20:23], v[74:75], off
	v_lshl_add_u64 v[32:33], v[56:57], 0, v[64:65]
	v_lshl_add_u64 v[42:43], v[48:49], 0, v[64:65]
	v_lshl_add_u64 v[50:51], v[40:41], 0, v[80:81]
	v_lshl_add_u64 v[58:59], v[48:49], 0, v[80:81]
	v_lshl_add_u64 v[82:83], v[56:57], 0, v[80:81]
	global_load_dwordx4 v[24:27], v[32:33], off offset:16
	global_load_dwordx4 v[28:31], v[32:33], off
	global_load_dwordx4 v[88:91], v[42:43], off offset:16
	global_load_dwordx4 v[84:87], v[42:43], off
	s_nop 0
	global_load_dwordx4 v[32:35], v[76:77], off offset:16
	global_load_dwordx4 v[36:39], v[76:77], off
	global_load_dwordx4 v[40:43], v[50:51], off offset:16
	global_load_dwordx4 v[44:47], v[50:51], off
	global_load_dwordx4 v[96:99], v[58:59], off offset:16
	global_load_dwordx4 v[92:95], v[58:59], off
	s_nop 0
	global_load_dwordx4 v[48:51], v[78:79], off offset:16
	global_load_dwordx4 v[52:55], v[78:79], off
	global_load_dwordx4 v[56:59], v[82:83], off offset:16
	global_load_dwordx4 v[60:63], v[82:83], off
	s_waitcnt vmcnt(11)
	v_pk_add_f32 v[88:89], v[88:89], 1.0 op_sel_hi:[1,0]
	s_waitcnt vmcnt(10)
	v_pk_add_f32 v[82:83], v[86:87], 1.0 op_sel_hi:[1,0]
	v_pk_add_f32 v[84:85], v[84:85], 1.0 op_sel_hi:[1,0]
	v_pk_add_f32 v[86:87], v[90:91], 1.0 op_sel_hi:[1,0]
	s_waitcnt vmcnt(4)
	v_pk_add_f32 v[90:91], v[94:95], 1.0 op_sel_hi:[1,0]
	v_pk_add_f32 v[92:93], v[92:93], 1.0 op_sel_hi:[1,0]
	v_pk_add_f32 v[94:95], v[98:99], 1.0 op_sel_hi:[1,0]
	v_pk_add_f32 v[96:97], v[96:97], 1.0 op_sel_hi:[1,0]
	v_mov_b32_e32 v98, v102
	v_ashrrev_i32_e32 v99, 31, v102
	s_mov_b64 s[60:61], 0x1000
	v_lshlrev_b64 v[98:99], 11, v[98:99]
	v_lshl_add_u64 v[122:123], v[68:69], 0, v[98:99]
	v_lshl_add_u64 v[118:119], v[66:67], 0, v[98:99]
	global_load_dwordx4 v[224:227], v[122:123], off
	global_load_dwordx4 v[228:231], v[122:123], off offset:1024
	global_load_dwordx4 v[232:235], v[118:119], off
	global_load_dwordx4 v[236:239], v[118:119], off offset:1024
	global_load_dwordx4 v[240:243], v[122:123], off offset:2048
	global_load_dwordx4 v[244:247], v[122:123], off offset:3072
	global_load_dwordx4 v[248:251], v[118:119], off offset:2048
	global_load_dwordx4 v[252:255], v[118:119], off offset:3072
	v_lshl_add_u64 v[122:123], v[122:123], 0, s[60:61]
	v_lshl_add_u64 v[118:119], v[118:119], 0, s[60:61]
	global_load_dwordx4 v[188:191], v[122:123], off
	global_load_dwordx4 v[192:195], v[122:123], off offset:1024
	global_load_dwordx4 v[196:199], v[118:119], off
	global_load_dwordx4 v[200:203], v[118:119], off offset:1024
	global_load_dwordx4 v[204:207], v[122:123], off offset:2048
	global_load_dwordx4 v[208:211], v[122:123], off offset:3072
	global_load_dwordx4 v[212:215], v[118:119], off offset:2048
	global_load_dwordx4 v[220:223], v[118:119], off offset:3072
.LBB0_1291:
	v_add_u32_e32 v98, s5, v102
	v_ashrrev_i32_e32 v99, 31, v98
	v_add_u32_e32 v100, 1, v98
	v_lshlrev_b64 v[98:99], 11, v[98:99]
	v_lshl_add_u64 v[122:123], v[68:69], 0, v[98:99]
	v_lshl_add_u64 v[118:119], v[66:67], 0, v[98:99]
	s_cmp_eq_u32 s5, 0
	s_cbranch_scc0 .Lrpfr11A_b
	s_waitcnt vmcnt(12)
	v_mov_b32_e32 v106, v224
	v_mov_b32_e32 v107, v225
	v_mov_b32_e32 v108, v226
	v_mov_b32_e32 v109, v227
	v_mov_b32_e32 v110, v228
	v_mov_b32_e32 v111, v229
	v_mov_b32_e32 v112, v230
	v_mov_b32_e32 v113, v231
	v_mov_b32_e32 v114, v232
	v_mov_b32_e32 v115, v233
	v_mov_b32_e32 v116, v234
	v_mov_b32_e32 v117, v235
	v_mov_b32_e32 v118, v236
	v_mov_b32_e32 v119, v237
	v_mov_b32_e32 v120, v238
	v_mov_b32_e32 v121, v239
	s_branch .Lrpfr11A_d

.Lrpfr11A_d:
	s_nop 0
	v_ashrrev_i32_e32 v101, 31, v100
	v_lshl_add_u64 v[124:125], v[70:71], 0, v[98:99]
	v_lshlrev_b64 v[98:99], 11, v[100:101]
	v_lshl_add_u64 v[100:101], v[68:69], 0, v[98:99]
	v_lshl_add_u64 v[126:127], v[66:67], 0, v[98:99]
	s_add_i32 s5, s5, 2
	s_cmp_eq_u32 s5, 4
	v_lshl_add_u64 v[98:99], v[70:71], 0, v[98:99]
	s_nop 0
	v_lshlrev_b32_e32 v128, 16, v106
	v_and_b32_e32 v129, 0xffff0000, v106
	s_nop 0
	v_and_b32_e32 v139, 0xffff0000, v116
	v_and_b32_e32 v138, 0xffff0000, v114
	v_lshlrev_b32_e32 v137, 16, v116
	v_lshlrev_b32_e32 v136, 16, v114
	v_lshlrev_b32_e32 v140, 16, v115
	v_and_b32_e32 v116, 0xffff0000, v115
	s_nop 0
	v_lshlrev_b32_e32 v115, 16, v118
	v_lshlrev_b32_e32 v114, 16, v120
	v_and_b32_e32 v143, 0xffff0000, v118
	v_and_b32_e32 v142, 0xffff0000, v120
	v_lshlrev_b32_e32 v148, 16, v121
	v_and_b32_e32 v118, 0xffff0000, v121
	v_pk_mul_f32 v[120:121], v[138:139], v[138:139]
	v_lshlrev_b32_e32 v141, 16, v117
	v_pk_mul_f32 v[150:151], v[142:143], v[142:143]
	v_pk_fma_f32 v[120:121], v[136:137], v[136:137], v[120:121]
	v_and_b32_e32 v117, 0xffff0000, v117
	v_lshlrev_b32_e32 v149, 16, v119
	v_mov_b32_e32 v154, v136
	v_mov_b32_e32 v155, v138
	v_mov_b32_e32 v138, v137
	v_pk_fma_f32 v[136:137], v[114:115], v[114:115], v[150:151]
	v_pk_fma_f32 v[120:121], v[140:141], v[140:141], v[120:121]
	v_and_b32_e32 v119, 0xffff0000, v119
	v_pk_fma_f32 v[136:137], v[148:149], v[148:149], v[136:137]
	v_pk_fma_f32 v[120:121], v[116:117], v[116:117], v[120:121]
	v_mov_b32_e32 v156, v149
	v_mov_b32_e32 v157, v119
	v_mov_b32_e32 v149, v118
	v_pk_fma_f32 v[118:119], v[118:119], v[118:119], v[136:137]
	v_add_f32_e32 v120, v120, v121
	v_add_f32_e32 v119, v120, v119
	v_add_f32_e32 v118, v118, v119
	ds_bpermute_b32 v119, v172, v118
	v_mov_b32_e32 v152, v140
	v_mov_b32_e32 v153, v116
	v_mov_b32_e32 v116, v141
	v_mov_b32_e32 v158, v115
	s_waitcnt lgkmcnt(0)
	v_add_f32_e32 v118, v118, v119
	ds_bpermute_b32 v119, v173, v118
	v_mov_b32_e32 v159, v143
	v_mov_b32_e32 v115, v142
	v_lshlrev_b32_e32 v106, 16, v107
	v_and_b32_e32 v107, 0xffff0000, v107
	s_waitcnt lgkmcnt(0)
	v_add_f32_e32 v118, v118, v119
	ds_bpermute_b32 v119, v174, v118
	v_lshlrev_b32_e32 v130, 16, v108
	v_and_b32_e32 v131, 0xffff0000, v108
	v_lshlrev_b32_e32 v108, 16, v109
	v_and_b32_e32 v109, 0xffff0000, v109
	s_waitcnt lgkmcnt(0)
	v_add_f32_e32 v118, v118, v119
	ds_bpermute_b32 v119, v175, v118
	v_lshlrev_b32_e32 v132, 16, v110
	v_and_b32_e32 v133, 0xffff0000, v110
	v_lshlrev_b32_e32 v110, 16, v111
	v_and_b32_e32 v111, 0xffff0000, v111
	s_waitcnt lgkmcnt(0)
	v_add_f32_e32 v118, v118, v119
	ds_bpermute_b32 v119, v176, v118
	v_lshlrev_b32_e32 v134, 16, v112
	v_and_b32_e32 v135, 0xffff0000, v112
	v_lshlrev_b32_e32 v112, 16, v113
	v_and_b32_e32 v113, 0xffff0000, v113
	s_waitcnt lgkmcnt(0)
	v_add_f32_e32 v118, v118, v119
	ds_bpermute_b32 v119, v177, v118
	s_waitcnt lgkmcnt(0)
	v_add_f32_e32 v118, v118, v119
	v_fmamk_f32 v118, v118, 0x3a800000, v104
	v_mul_f32_e32 v119, 0x4b800000, v118
	v_cmp_gt_f32_e32 vcc, s3, v118
	s_nop 1
	v_cndmask_b32_e32 v118, v118, v119, vcc
	v_rsq_f32_e32 v118, v118
	s_nop 0
	v_mul_f32_e32 v119, 0x45800000, v118
	v_cndmask_b32_e32 v118, v118, v119, vcc
	v_pk_mul_f32 v[120:121], v[118:119], v[152:153] op_sel_hi:[0,1]
	v_pk_mul_f32 v[136:137], v[118:119], v[154:155] op_sel_hi:[0,1]
	v_pk_mul_f32 v[116:117], v[118:119], v[116:117] op_sel_hi:[0,1]
	v_pk_mul_f32 v[138:139], v[118:119], v[138:139] op_sel_hi:[0,1]
	v_pk_mul_f32 v[140:141], v[118:119], v[156:157] op_sel_hi:[0,1]
	v_pk_mul_f32 v[142:143], v[118:119], v[158:159] op_sel_hi:[0,1]
	v_pk_mul_f32 v[148:149], v[118:119], v[148:149] op_sel_hi:[0,1]
	v_pk_mul_f32 v[114:115], v[118:119], v[114:115] op_sel_hi:[0,1]
	v_pk_mul_f32 v[118:119], v[4:5], v[136:137]
	v_pk_mul_f32 v[120:121], v[6:7], v[120:121]
	v_pk_mul_f32 v[136:137], v[0:1], v[138:139]
	v_pk_mul_f32 v[116:117], v[2:3], v[116:117]
	v_pk_mul_f32 v[138:139], v[36:37], v[142:143]
	v_pk_mul_f32 v[140:141], v[38:39], v[140:141]
	v_pk_mul_f32 v[114:115], v[32:33], v[114:115]
	v_pk_mul_f32 v[142:143], v[34:35], v[148:149]
	v_pk_fma_f32 v[120:121], v[14:15], v[120:121], v[106:107]
	v_pk_fma_f32 v[118:119], v[12:13], v[118:119], v[128:129]
	v_pk_fma_f32 v[116:117], v[10:11], v[116:117], v[108:109]
	v_pk_fma_f32 v[128:129], v[8:9], v[136:137], v[130:131]
	v_pk_fma_f32 v[130:131], v[46:47], v[140:141], v[110:111]
	v_pk_fma_f32 v[132:133], v[44:45], v[138:139], v[132:133]
	v_pk_fma_f32 v[136:137], v[42:43], v[142:143], v[112:113]
	v_pk_fma_f32 v[114:115], v[40:41], v[114:115], v[134:135]
	v_cvt_pk_bf16_f32 v106, v118, v119
	v_cvt_pk_bf16_f32 v107, v120, v121
	v_cvt_pk_bf16_f32 v108, v128, v129
	v_cvt_pk_bf16_f32 v109, v116, v117
	v_mov_b32_e32 v138, v119
	v_mov_b32_e32 v139, v129
	v_cvt_pk_bf16_f32 v110, v132, v133
	v_cvt_pk_bf16_f32 v111, v130, v131
	v_cvt_pk_bf16_f32 v112, v114, v115
	v_cvt_pk_bf16_f32 v113, v136, v137
	v_mov_b32_e32 v134, v118
	v_mov_b32_e32 v135, v128
	v_mov_b32_e32 v150, v115
	v_mov_b32_e32 v151, v133
	global_store_dwordx4 v[122:123], v[106:109], off sc1
	global_store_dwordx4 v[122:123], v[110:113], off offset:1024 sc1
	v_mov_b32_e32 v140, v120
	v_pk_mul_f32 v[106:107], v[138:139], v[138:139]
	v_mov_b32_e32 v141, v116
	v_mov_b32_e32 v148, v114
	v_mov_b32_e32 v149, v132
	v_pk_mul_f32 v[108:109], v[150:151], v[150:151]
	v_pk_fma_f32 v[106:107], v[134:135], v[134:135], v[106:107]
	v_mov_b32_e32 v142, v121
	v_mov_b32_e32 v143, v117
	v_mov_b32_e32 v152, v136
	v_mov_b32_e32 v153, v130
	v_pk_fma_f32 v[108:109], v[148:149], v[148:149], v[108:109]
	v_pk_fma_f32 v[106:107], v[140:141], v[140:141], v[106:107]
	v_mov_b32_e32 v154, v137
	v_mov_b32_e32 v155, v131
	v_pk_fma_f32 v[108:109], v[152:153], v[152:153], v[108:109]
	v_pk_fma_f32 v[106:107], v[142:143], v[142:143], v[106:107]
	v_pk_fma_f32 v[108:109], v[154:155], v[154:155], v[108:109]
	v_add_f32_e32 v106, v106, v107
	v_add_f32_e32 v106, v109, v106
	v_add_f32_e32 v106, v108, v106
	ds_bpermute_b32 v107, v172, v106
	s_waitcnt lgkmcnt(0)
	v_add_f32_e32 v106, v106, v107
	ds_bpermute_b32 v107, v173, v106
	s_waitcnt lgkmcnt(0)
	v_add_f32_e32 v106, v106, v107
	ds_bpermute_b32 v107, v174, v106
	s_waitcnt lgkmcnt(0)
	v_add_f32_e32 v106, v106, v107
	ds_bpermute_b32 v107, v175, v106
	s_waitcnt lgkmcnt(0)
	v_add_f32_e32 v106, v106, v107
	ds_bpermute_b32 v107, v176, v106
	s_waitcnt lgkmcnt(0)
	v_add_f32_e32 v106, v106, v107
	ds_bpermute_b32 v107, v177, v106
	s_waitcnt lgkmcnt(0)
	v_add_f32_e32 v106, v106, v107
	v_fmamk_f32 v106, v106, 0x3a800000, v104
	v_mul_f32_e32 v107, 0x4b800000, v106
	v_cmp_gt_f32_e32 vcc, s3, v106
	s_nop 1
	v_cndmask_b32_e32 v106, v106, v107, vcc
	v_rsq_f32_e32 v106, v106
	s_nop 0
	v_mul_f32_e32 v107, 0x45800000, v106
	v_cndmask_b32_e32 v106, v106, v107, vcc
	v_pk_mul_f32 v[108:109], v[120:121], v[106:107] op_sel_hi:[1,0]
	v_pk_mul_f32 v[110:111], v[118:119], v[106:107] op_sel_hi:[1,0]
	v_pk_mul_f32 v[112:113], v[116:117], v[106:107] op_sel_hi:[1,0]
	v_pk_mul_f32 v[116:117], v[128:129], v[106:107] op_sel_hi:[1,0]
	v_pk_mul_f32 v[118:119], v[130:131], v[106:107] op_sel_hi:[1,0]
	v_pk_mul_f32 v[120:121], v[132:133], v[106:107] op_sel_hi:[1,0]
	v_pk_mul_f32 v[122:123], v[136:137], v[106:107] op_sel_hi:[1,0]
	v_pk_mul_f32 v[106:107], v[114:115], v[106:107] op_sel_hi:[1,0]
	v_pk_mul_f32 v[110:111], v[20:21], v[110:111]
	v_pk_mul_f32 v[108:109], v[22:23], v[108:109]
	v_pk_mul_f32 v[114:115], v[16:17], v[116:117]
	v_pk_mul_f32 v[112:113], v[18:19], v[112:113]
	v_pk_mul_f32 v[116:117], v[52:53], v[120:121]
	v_pk_mul_f32 v[118:119], v[54:55], v[118:119]
	v_pk_mul_f32 v[106:107], v[48:49], v[106:107]
	v_pk_mul_f32 v[120:121], v[50:51], v[122:123]
	v_pk_fma_f32 v[108:109], v[82:83], v[108:109], v[30:31]
	v_pk_fma_f32 v[110:111], v[84:85], v[110:111], v[28:29]
	v_pk_fma_f32 v[112:113], v[86:87], v[112:113], v[26:27]
	v_pk_fma_f32 v[114:115], v[88:89], v[114:115], v[24:25]
	v_pk_fma_f32 v[118:119], v[90:91], v[118:119], v[62:63]
	v_pk_fma_f32 v[116:117], v[92:93], v[116:117], v[60:61]
	v_pk_fma_f32 v[120:121], v[94:95], v[120:121], v[58:59]
	v_pk_fma_f32 v[122:123], v[96:97], v[106:107], v[56:57]
	v_cvt_pk_bf16_f32 v106, v110, v111
	v_cvt_pk_bf16_f32 v107, v108, v109
	v_cvt_pk_bf16_f32 v108, v114, v115
	v_cvt_pk_bf16_f32 v109, v112, v113
	v_cvt_pk_bf16_f32 v110, v116, v117
	v_cvt_pk_bf16_f32 v111, v118, v119
	v_cvt_pk_bf16_f32 v112, v122, v123
	v_cvt_pk_bf16_f32 v113, v120, v121
	global_store_dwordx4 v[124:125], v[106:109], off sc1
	global_store_dwordx4 v[124:125], v[110:113], off offset:1024 sc1
	s_cselect_b32 s62, 1, 0
	s_cmp_eq_u32 s5, 2
	s_cbranch_scc0 .Lrpfr11B_b
	s_waitcnt vmcnt(12)
	v_mov_b32_e32 v106, v240
	v_mov_b32_e32 v107, v241
	v_mov_b32_e32 v108, v242
	v_mov_b32_e32 v109, v243
	v_mov_b32_e32 v110, v244
	v_mov_b32_e32 v111, v245
	v_mov_b32_e32 v112, v246
	v_mov_b32_e32 v113, v247
	v_mov_b32_e32 v114, v248
	v_mov_b32_e32 v115, v249
	v_mov_b32_e32 v116, v250
	v_mov_b32_e32 v117, v251
	v_mov_b32_e32 v118, v252
	v_mov_b32_e32 v119, v253
	v_mov_b32_e32 v120, v254
	v_mov_b32_e32 v121, v255
	s_branch .Lrpfr11B_d

.Lrpfr11B_d:
	s_cmp_lg_u32 s62, 0
	s_nop 0
	s_nop 0
	v_lshlrev_b32_e32 v122, 16, v106
	v_and_b32_e32 v123, 0xffff0000, v106
	s_nop 0
	v_and_b32_e32 v133, 0xffff0000, v116
	v_and_b32_e32 v132, 0xffff0000, v114
	v_lshlrev_b32_e32 v131, 16, v116
	v_lshlrev_b32_e32 v130, 16, v114
	v_lshlrev_b32_e32 v134, 16, v115
	v_and_b32_e32 v116, 0xffff0000, v115
	s_nop 0
	v_lshlrev_b32_e32 v115, 16, v118
	v_lshlrev_b32_e32 v114, 16, v120
	v_and_b32_e32 v137, 0xffff0000, v118
	v_and_b32_e32 v136, 0xffff0000, v120
	v_lshlrev_b32_e32 v138, 16, v121
	v_and_b32_e32 v118, 0xffff0000, v121
	v_pk_mul_f32 v[120:121], v[132:133], v[132:133]
	v_lshlrev_b32_e32 v135, 16, v117
	v_pk_mul_f32 v[140:141], v[136:137], v[136:137]
	v_pk_fma_f32 v[120:121], v[130:131], v[130:131], v[120:121]
	v_and_b32_e32 v117, 0xffff0000, v117
	v_lshlrev_b32_e32 v139, 16, v119
	v_mov_b32_e32 v148, v130
	v_mov_b32_e32 v149, v132
	v_mov_b32_e32 v132, v131
	v_pk_fma_f32 v[130:131], v[114:115], v[114:115], v[140:141]
	v_pk_fma_f32 v[120:121], v[134:135], v[134:135], v[120:121]
	v_and_b32_e32 v119, 0xffff0000, v119
	v_pk_fma_f32 v[130:131], v[138:139], v[138:139], v[130:131]
	v_pk_fma_f32 v[120:121], v[116:117], v[116:117], v[120:121]
	v_mov_b32_e32 v150, v139
	v_mov_b32_e32 v151, v119
	v_mov_b32_e32 v139, v118
	v_pk_fma_f32 v[118:119], v[118:119], v[118:119], v[130:131]
	v_add_f32_e32 v120, v120, v121
	v_add_f32_e32 v119, v120, v119
	v_add_f32_e32 v118, v118, v119
	ds_bpermute_b32 v119, v172, v118
	v_mov_b32_e32 v142, v134
	v_mov_b32_e32 v143, v116
	v_mov_b32_e32 v116, v135
	v_mov_b32_e32 v152, v115
	s_waitcnt lgkmcnt(0)
	v_add_f32_e32 v118, v118, v119
	ds_bpermute_b32 v119, v173, v118
	v_mov_b32_e32 v153, v137
	v_mov_b32_e32 v115, v136
	v_lshlrev_b32_e32 v106, 16, v107
	v_and_b32_e32 v107, 0xffff0000, v107
	s_waitcnt lgkmcnt(0)
	v_add_f32_e32 v118, v118, v119
	ds_bpermute_b32 v119, v174, v118
	v_lshlrev_b32_e32 v124, 16, v108
	v_and_b32_e32 v125, 0xffff0000, v108
	v_lshlrev_b32_e32 v108, 16, v109
	v_and_b32_e32 v109, 0xffff0000, v109
	s_waitcnt lgkmcnt(0)
	v_add_f32_e32 v118, v118, v119
	ds_bpermute_b32 v119, v175, v118
	v_lshlrev_b32_e32 v126, 16, v110
	v_and_b32_e32 v127, 0xffff0000, v110
	v_lshlrev_b32_e32 v110, 16, v111
	v_and_b32_e32 v111, 0xffff0000, v111
	s_waitcnt lgkmcnt(0)
	v_add_f32_e32 v118, v118, v119
	ds_bpermute_b32 v119, v176, v118
	v_lshlrev_b32_e32 v128, 16, v112
	v_and_b32_e32 v129, 0xffff0000, v112
	v_lshlrev_b32_e32 v112, 16, v113
	v_and_b32_e32 v113, 0xffff0000, v113
	s_waitcnt lgkmcnt(0)
	v_add_f32_e32 v118, v118, v119
	ds_bpermute_b32 v119, v177, v118
	s_waitcnt lgkmcnt(0)
	v_add_f32_e32 v118, v118, v119
	v_fmamk_f32 v118, v118, 0x3a800000, v104
	v_mul_f32_e32 v119, 0x4b800000, v118
	v_cmp_gt_f32_e32 vcc, s3, v118
	s_nop 1
	v_cndmask_b32_e32 v118, v118, v119, vcc
	v_rsq_f32_e32 v118, v118
	s_nop 0
	v_mul_f32_e32 v119, 0x45800000, v118
	v_cndmask_b32_e32 v118, v118, v119, vcc
	v_pk_mul_f32 v[120:121], v[118:119], v[142:143] op_sel_hi:[0,1]
	v_pk_mul_f32 v[130:131], v[118:119], v[148:149] op_sel_hi:[0,1]
	v_pk_mul_f32 v[116:117], v[118:119], v[116:117] op_sel_hi:[0,1]
	v_pk_mul_f32 v[132:133], v[118:119], v[132:133] op_sel_hi:[0,1]
	v_pk_mul_f32 v[134:135], v[118:119], v[150:151] op_sel_hi:[0,1]
	v_pk_mul_f32 v[136:137], v[118:119], v[152:153] op_sel_hi:[0,1]
	v_pk_mul_f32 v[138:139], v[118:119], v[138:139] op_sel_hi:[0,1]
	v_pk_mul_f32 v[114:115], v[118:119], v[114:115] op_sel_hi:[0,1]
	v_pk_mul_f32 v[118:119], v[4:5], v[130:131]
	v_pk_mul_f32 v[120:121], v[6:7], v[120:121]
	v_pk_mul_f32 v[130:131], v[0:1], v[132:133]
	v_pk_mul_f32 v[116:117], v[2:3], v[116:117]
	v_pk_mul_f32 v[132:133], v[36:37], v[136:137]
	v_pk_mul_f32 v[134:135], v[38:39], v[134:135]
	v_pk_mul_f32 v[114:115], v[32:33], v[114:115]
	v_pk_mul_f32 v[136:137], v[34:35], v[138:139]
	v_pk_fma_f32 v[120:121], v[14:15], v[120:121], v[106:107]
	v_pk_fma_f32 v[118:119], v[12:13], v[118:119], v[122:123]
	v_pk_fma_f32 v[116:117], v[10:11], v[116:117], v[108:109]
	v_pk_fma_f32 v[122:123], v[8:9], v[130:131], v[124:125]
	v_pk_fma_f32 v[124:125], v[46:47], v[134:135], v[110:111]
	v_pk_fma_f32 v[126:127], v[44:45], v[132:133], v[126:127]
	v_pk_fma_f32 v[130:131], v[42:43], v[136:137], v[112:113]
	v_pk_fma_f32 v[114:115], v[40:41], v[114:115], v[128:129]
	v_cvt_pk_bf16_f32 v106, v118, v119
	v_cvt_pk_bf16_f32 v107, v120, v121
	v_cvt_pk_bf16_f32 v108, v122, v123
	v_cvt_pk_bf16_f32 v109, v116, v117
	v_mov_b32_e32 v132, v119
	v_mov_b32_e32 v133, v123
	v_cvt_pk_bf16_f32 v110, v126, v127
	v_cvt_pk_bf16_f32 v111, v124, v125
	v_cvt_pk_bf16_f32 v112, v114, v115
	v_cvt_pk_bf16_f32 v113, v130, v131
	v_mov_b32_e32 v128, v118
	v_mov_b32_e32 v129, v122
	v_mov_b32_e32 v140, v115
	v_mov_b32_e32 v141, v127
	global_store_dwordx4 v[100:101], v[106:109], off sc1
	global_store_dwordx4 v[100:101], v[110:113], off offset:1024 sc1
	v_pk_mul_f32 v[100:101], v[132:133], v[132:133]
	v_mov_b32_e32 v134, v120
	v_mov_b32_e32 v135, v116
	v_mov_b32_e32 v138, v114
	v_mov_b32_e32 v139, v126
	v_pk_mul_f32 v[106:107], v[140:141], v[140:141]
	v_pk_fma_f32 v[100:101], v[128:129], v[128:129], v[100:101]
	v_mov_b32_e32 v136, v121
	v_mov_b32_e32 v137, v117
	v_mov_b32_e32 v142, v130
	v_mov_b32_e32 v143, v124
	v_pk_fma_f32 v[106:107], v[138:139], v[138:139], v[106:107]
	v_pk_fma_f32 v[100:101], v[134:135], v[134:135], v[100:101]
	v_mov_b32_e32 v148, v131
	v_mov_b32_e32 v149, v125
	v_pk_fma_f32 v[106:107], v[142:143], v[142:143], v[106:107]
	v_pk_fma_f32 v[100:101], v[136:137], v[136:137], v[100:101]
	v_pk_fma_f32 v[106:107], v[148:149], v[148:149], v[106:107]
	v_add_f32_e32 v100, v100, v101
	v_add_f32_e32 v100, v107, v100
	v_add_f32_e32 v100, v106, v100
	ds_bpermute_b32 v101, v172, v100
	s_waitcnt lgkmcnt(0)
	v_add_f32_e32 v100, v100, v101
	ds_bpermute_b32 v101, v173, v100
	s_waitcnt lgkmcnt(0)
	v_add_f32_e32 v100, v100, v101
	ds_bpermute_b32 v101, v174, v100
	s_waitcnt lgkmcnt(0)
	v_add_f32_e32 v100, v100, v101
	ds_bpermute_b32 v101, v175, v100
	s_waitcnt lgkmcnt(0)
	v_add_f32_e32 v100, v100, v101
	ds_bpermute_b32 v101, v176, v100
	s_waitcnt lgkmcnt(0)
	v_add_f32_e32 v100, v100, v101
	ds_bpermute_b32 v101, v177, v100
	s_waitcnt lgkmcnt(0)
	v_add_f32_e32 v100, v100, v101
	v_fmamk_f32 v100, v100, 0x3a800000, v104
	v_mul_f32_e32 v101, 0x4b800000, v100
	v_cmp_gt_f32_e32 vcc, s3, v100
	s_nop 1
	v_cndmask_b32_e32 v100, v100, v101, vcc
	v_rsq_f32_e32 v100, v100
	s_nop 0
	v_mul_f32_e32 v101, 0x45800000, v100
	v_cndmask_b32_e32 v100, v100, v101, vcc
	v_pk_mul_f32 v[106:107], v[120:121], v[100:101] op_sel_hi:[1,0]
	v_pk_mul_f32 v[108:109], v[118:119], v[100:101] op_sel_hi:[1,0]
	v_pk_mul_f32 v[110:111], v[116:117], v[100:101] op_sel_hi:[1,0]
	v_pk_mul_f32 v[112:113], v[122:123], v[100:101] op_sel_hi:[1,0]
	v_pk_mul_f32 v[116:117], v[124:125], v[100:101] op_sel_hi:[1,0]
	v_pk_mul_f32 v[118:119], v[126:127], v[100:101] op_sel_hi:[1,0]
	v_pk_mul_f32 v[120:121], v[130:131], v[100:101] op_sel_hi:[1,0]
	v_pk_mul_f32 v[100:101], v[114:115], v[100:101] op_sel_hi:[1,0]
	v_pk_mul_f32 v[108:109], v[20:21], v[108:109]
	v_pk_mul_f32 v[106:107], v[22:23], v[106:107]
	v_pk_mul_f32 v[112:113], v[16:17], v[112:113]
	v_pk_mul_f32 v[110:111], v[18:19], v[110:111]
	v_pk_mul_f32 v[114:115], v[52:53], v[118:119]
	v_pk_mul_f32 v[116:117], v[54:55], v[116:117]
	v_pk_mul_f32 v[100:101], v[48:49], v[100:101]
	v_pk_mul_f32 v[118:119], v[50:51], v[120:121]
	v_pk_fma_f32 v[120:121], v[82:83], v[106:107], v[30:31]
	v_pk_fma_f32 v[106:107], v[84:85], v[108:109], v[28:29]
	v_pk_fma_f32 v[110:111], v[86:87], v[110:111], v[26:27]
	v_pk_fma_f32 v[108:109], v[88:89], v[112:113], v[24:25]
	v_pk_fma_f32 v[112:113], v[90:91], v[116:117], v[62:63]
	v_pk_fma_f32 v[114:115], v[92:93], v[114:115], v[60:61]
	v_pk_fma_f32 v[116:117], v[94:95], v[118:119], v[58:59]
	v_pk_fma_f32 v[100:101], v[96:97], v[100:101], v[56:57]
	v_cvt_pk_bf16_f32 v106, v106, v107
	v_cvt_pk_bf16_f32 v107, v120, v121
	v_cvt_pk_bf16_f32 v108, v108, v109
	v_cvt_pk_bf16_f32 v109, v110, v111
	v_cvt_pk_bf16_f32 v110, v114, v115
	v_cvt_pk_bf16_f32 v111, v112, v113
	v_cvt_pk_bf16_f32 v112, v100, v101
	v_cvt_pk_bf16_f32 v113, v116, v117
	global_store_dwordx4 v[98:99], v[106:109], off sc1
	global_store_dwordx4 v[98:99], v[110:113], off offset:1024 sc1
	s_cbranch_scc0 .LBB0_1291
	v_add_u32_e32 v105, s0, v105
	v_cmp_lt_i32_e32 vcc, s4, v105
	s_or_b64 s[8:9], vcc, s[8:9]
	v_add_u32_e32 v102, s1, v102
	s_andn2_b64 exec, exec, s[8:9]
	s_cbranch_execnz .LBB0_1290

	.amdhsa_kernel _Z4mega6Params
		.amdhsa_group_segment_fixed_size 0
		.amdhsa_private_segment_fixed_size 0
		.amdhsa_kernarg_size 440
		.amdhsa_user_sgpr_count 2
		.amdhsa_user_sgpr_dispatch_ptr 0
		.amdhsa_user_sgpr_queue_ptr 0
		.amdhsa_user_sgpr_kernarg_segment_ptr 1
		.amdhsa_user_sgpr_dispatch_id 0
		.amdhsa_user_sgpr_kernarg_preload_length 0
		.amdhsa_user_sgpr_kernarg_preload_offset 0
		.amdhsa_user_sgpr_private_segment_size 0
		.amdhsa_uses_dynamic_stack 0
		.amdhsa_enable_private_segment 0
		.amdhsa_system_sgpr_workgroup_id_x 1
		.amdhsa_system_sgpr_workgroup_id_y 0
		.amdhsa_system_sgpr_workgroup_id_z 0
		.amdhsa_system_sgpr_workgroup_info 0
		.amdhsa_system_vgpr_workitem_id 2
		.amdhsa_next_free_vgpr 256
		.amdhsa_next_free_sgpr 102
		.amdhsa_accum_offset 256
		.amdhsa_reserve_vcc 1
		.amdhsa_float_round_mode_32 0
		.amdhsa_float_round_mode_16_64 0
		.amdhsa_float_denorm_mode_32 3
		.amdhsa_float_denorm_mode_16_64 3
		.amdhsa_dx10_clamp 1
		.amdhsa_ieee_mode 1
		.amdhsa_fp16_overflow 0
		.amdhsa_tg_split 0
		.amdhsa_exception_fp_ieee_invalid_op 0
		.amdhsa_exception_fp_denorm_src 0
		.amdhsa_exception_fp_ieee_div_zero 0
		.amdhsa_exception_fp_ieee_overflow 0
		.amdhsa_exception_fp_ieee_underflow 0
		.amdhsa_exception_fp_ieee_inexact 0
		.amdhsa_exception_int_div_zero 0
	.end_amdhsa_kernel

amdhsa.kernels:
  - .agpr_count:     0
    .args:
      - .offset:         0
        .size:           184
        .value_kind:     by_value
      - .offset:         184
        .size:           4
        .value_kind:     hidden_block_count_x
      - .offset:         188
        .size:           4
        .value_kind:     hidden_block_count_y
      - .offset:         192
        .size:           4
        .value_kind:     hidden_block_count_z
      - .offset:         196
        .size:           2
        .value_kind:     hidden_group_size_x
      - .offset:         198
        .size:           2
        .value_kind:     hidden_group_size_y
      - .offset:         200
        .size:           2
        .value_kind:     hidden_group_size_z
      - .offset:         202
        .size:           2
        .value_kind:     hidden_remainder_x
      - .offset:         204
        .size:           2
        .value_kind:     hidden_remainder_y
      - .offset:         206
        .size:           2
        .value_kind:     hidden_remainder_z
      - .offset:         224
        .size:           8
        .value_kind:     hidden_global_offset_x
      - .offset:         232
        .size:           8
        .value_kind:     hidden_global_offset_y
      - .offset:         240
        .size:           8
        .value_kind:     hidden_global_offset_z
      - .offset:         248
        .size:           2
        .value_kind:     hidden_grid_dims
      - .offset:         272
        .size:           8
        .value_kind:     hidden_multigrid_sync_arg
      - .offset:         304
        .size:           4
        .value_kind:     hidden_dynamic_lds_size
    .group_segment_fixed_size: 0
    .kernarg_segment_align: 8
    .kernarg_segment_size: 440
    .language:       OpenCL C
    .language_version:
      - 2
      - 0
    .max_flat_workgroup_size: 512
    .name:           _Z4mega6Params
    .private_segment_fixed_size: 0
    .sgpr_count:     108
    .sgpr_spill_count: 82
    .symbol:         _Z4mega6Params.kd
    .uniform_work_group_size: 1
    .uses_dynamic_stack: false
    .vgpr_count:     256
    .vgpr_spill_count: 0
    .wavefront_size: 64
